# row pass: the row-after-next fp16 residual and F loads are issued right after their registers are consumed (about one row-process earlier)
# speedup vs baseline: 1.0038x; 1.0038x over previous
; #define UNPK_BF(dst, SRC_) do { const u32x4 t_ = (SRC_); dst[0] = bflo(t_.x); dst[1] = bfhi(t_.x); dst[2] = bflo(t_.y); dst[3] = bfhi(t_.y); dst[4] = bflo(t_.z); dst[5] = bfhi(t_.z); dst[6] = bflo(t_.w); dst[7] = bfhi(t_.w); } while (0)
; __device__ __forceinline__ void row_load(const RowArgs& R, int m, int lane, RowRaw& q) {
;     const size_t off = (size_t)m * DM + 8 * lane;
;     if (R.hin32) {
; #pragma unroll
;         for (int j = 0; j < 2; ++j) { q.v32[j][0] = __builtin_nontemporal_load((const f32x4*)(R.hin32 + off + 512 * j)); q.v32[j][1] = __builtin_nontemporal_load((const f32x4*)(R.hin32 + off + 512 * j + 4)); }
;     } else {
; #pragma unroll
;         for (int j = 0; j < 2; ++j) q.v16[j] = __builtin_nontemporal_load((const u32x4*)(R.hin16 + off + 512 * j));
;     }
;     if (R.F) {
; #pragma unroll
;         for (int j = 0; j < 2; ++j) q.f[j] = __builtin_nontemporal_load((const u32x4*)(R.F + off + 512 * j));
;     }
; __device__ __forceinline__ void row_process(const RowArgs& R, int m, int lane, const RowRaw& q, const float (&gp)[2][8], const float (&gn)[2][8], const f32x4 bf, const LAS f32x4* afl) {
;     ...
;         for (int j = 0; j < 2; ++j) UNPK_BF(f[j], q.f[j]);
;         if (R.F2) {
;             float e[2][8]; float ss = 0.f;
; #pragma unroll
;             for (int j = 0; j < 2; ++j) { UNPK_BF(e[j], q.e[j]);
; #pragma unroll
;                 for (int c = 0; c < 8; ++c) ss += e[j][c] * e[j][c]; }
;             const float r = 1.0f / sqrtf(wave_sum(ss) * (1.0f / DM) + EPS);
; #pragma unroll
;             for (int j = 0; j < 2; ++j)
; #pragma unroll
;                 for (int c = 0; c < 8; ++c) v[j][c] += (1.0f / (1.0f + expf(-f[j][c]))) * (e[j][c] * r * gp[j][c]);
.LBB0_262:
	s_waitcnt vmcnt(10)
	v_and_b32_e32 v0, 0xffff0000, v72
	v_lshlrev_b32_e32 v149, 16, v73
	v_lshlrev_b32_e32 v148, 16, v72
	v_and_b32_e32 v151, 0xffff0000, v74
	v_and_b32_e32 v150, 0xffff0000, v73
	v_lshlrev_b32_e32 v153, 16, v75
	v_lshlrev_b32_e32 v152, 16, v74
	v_lshlrev_b32_e32 v156, 16, v76
	v_and_b32_e32 v157, 0xffff0000, v76
	v_lshlrev_b32_e32 v158, 16, v77
	v_and_b32_e32 v159, 0xffff0000, v77
	v_lshlrev_b32_e32 v160, 16, v78
	v_and_b32_e32 v161, 0xffff0000, v78
	v_and_b32_e32 v163, 0xffff0000, v75
	v_lshlrev_b32_e32 v162, 16, v79
	v_and_b32_e32 v154, 0xffff0000, v79
	s_and_b64 vcc, exec, s[12:13]
	s_cbranch_vccz .Lrp_early_done
	s_add_i32 s98, s89, s68
	s_cmp_gt_i32 s98, 0xffff
	s_cbranch_scc1 .Lrp_early_done
	s_ashr_i32 s99, s98, 31
	s_lshl_b64 s[98:99], s[98:99], 10
	v_mov_b32_e32 v39, s99
	v_or_b32_e32 v38, s98, v142
	v_lshl_add_u64 v[48:49], v[38:39], 1, s[46:47]
	global_load_dwordx4 v[44:47], v[48:49], off nt
	s_nop 0
	global_load_dwordx4 v[48:51], v[48:49], off offset:1024 nt
	v_lshl_add_u64 v[36:37], v[38:39], 1, s[20:21]
	global_load_dwordx4 v[72:75], v[36:37], off nt
	global_load_dwordx4 v[76:79], v[36:37], off offset:1024 nt
.Lrp_early_done:
	s_and_b64 vcc, exec, s[36:37]
	s_cbranch_vccz .LBB0_302
	v_mul_f32_e32 v155, 0xbfb8aa3b, v148
	v_rndne_f32_e32 v165, v155
	v_sub_f32_e32 v166, v155, v165
	v_fma_f32 v155, v148, s22, -v155
	v_fmac_f32_e32 v155, 0xb2a5705f, v148
	v_add_f32_e32 v155, v166, v155
	v_exp_f32_e32 v155, v155
	v_cvt_i32_f32_e32 v165, v165
	v_cmp_nlt_f32_e32 vcc, s55, v148
	s_mov_b32 s4, 0xc2b17218
	v_lshlrev_b32_e32 v207, 16, v61
	v_ldexp_f32 v155, v155, v165
	v_cndmask_b32_e32 v155, 0, v155, vcc
	v_cmp_ngt_f32_e32 vcc, s4, v148
	v_lshlrev_b32_e32 v206, 16, v60
	v_and_b32_e32 v143, 0xffff0000, v60
	v_cndmask_b32_e32 v166, v235, v155, vcc
	v_mul_f32_e32 v155, 0xbfb8aa3b, v0
	v_rndne_f32_e32 v165, v155
	v_sub_f32_e32 v167, v155, v165
	v_fma_f32 v155, v0, s22, -v155
	v_fmac_f32_e32 v155, 0xb2a5705f, v0
	v_add_f32_e32 v155, v167, v155
	v_exp_f32_e32 v155, v155
	v_cvt_i32_f32_e32 v165, v165
	v_cmp_nlt_f32_e32 vcc, s55, v0
	v_and_b32_e32 v164, 0xffff0000, v67
	v_pk_mul_f32 v[208:209], v[206:207], v[206:207]
	v_ldexp_f32 v155, v155, v165
	v_mul_f32_e32 v165, 0xbfb8aa3b, v149
	v_rndne_f32_e32 v167, v165
	v_sub_f32_e32 v168, v165, v167
	v_fma_f32 v165, v149, s22, -v165
	v_fmac_f32_e32 v165, 0xb2a5705f, v149
	v_add_f32_e32 v165, v168, v165
	v_exp_f32_e32 v165, v165
	v_cvt_i32_f32_e32 v167, v167
	v_cndmask_b32_e32 v155, 0, v155, vcc
	v_cmp_ngt_f32_e32 vcc, s4, v0
	v_lshlrev_b32_e32 v203, 16, v63
	v_ldexp_f32 v165, v165, v167
	v_cndmask_b32_e32 v155, v235, v155, vcc
	v_cmp_nlt_f32_e32 vcc, s55, v149
	v_lshlrev_b32_e32 v202, 16, v62
	v_pk_mul_f32 v[204:205], v[202:203], v[202:203]
	v_cndmask_b32_e32 v165, 0, v165, vcc
	v_cmp_ngt_f32_e32 vcc, s4, v149
	v_lshlrev_b32_e32 v176, 16, v65
	v_and_b32_e32 v177, 0xffff0000, v65
	v_cndmask_b32_e32 v167, v235, v165, vcc
	v_pk_add_f32 v[166:167], v[166:167], 1.0 op_sel_hi:[1,0]
	v_pk_mul_f32 v[186:187], v[176:177], v[176:177]
	v_div_scale_f32 v165, s[14:15], v167, v167, 1.0
	v_rcp_f32_e32 v168, v165
	v_add_f32_e32 v155, 1.0, v155
	v_fma_f32 v169, -v165, v168, 1.0
	v_fmac_f32_e32 v168, v169, v168
	v_div_scale_f32 v169, vcc, 1.0, v167, 1.0
	v_mul_f32_e32 v170, v169, v168
	v_fma_f32 v171, -v165, v170, v169
	v_fmac_f32_e32 v170, v171, v168
	v_fma_f32 v165, -v165, v170, v169
	v_div_fmas_f32 v165, v165, v168, v170
	v_div_fixup_f32 v167, v165, v167, 1.0
	v_div_scale_f32 v165, s[14:15], v166, v166, 1.0
	v_rcp_f32_e32 v168, v165
	s_nop 0
	v_fma_f32 v169, -v165, v168, 1.0
	v_fmac_f32_e32 v168, v169, v168
	v_div_scale_f32 v169, vcc, 1.0, v166, 1.0
	v_mul_f32_e32 v170, v169, v168
	v_fma_f32 v171, -v165, v170, v169
	v_fmac_f32_e32 v170, v171, v168
	v_fma_f32 v165, -v165, v170, v169
	v_div_fmas_f32 v165, v165, v168, v170
	v_div_fixup_f32 v166, v165, v166, 1.0
	v_mul_f32_e32 v165, 0xbfb8aa3b, v150
	v_rndne_f32_e32 v168, v165
	v_sub_f32_e32 v169, v165, v168
	v_fma_f32 v165, v150, s22, -v165
	v_fmac_f32_e32 v165, 0xb2a5705f, v150
	v_add_f32_e32 v165, v169, v165
	v_exp_f32_e32 v165, v165
	v_cvt_i32_f32_e32 v168, v168
	v_cmp_nlt_f32_e32 vcc, s55, v150
	v_ldexp_f32 v165, v165, v168
	s_nop 0
	v_cndmask_b32_e32 v165, 0, v165, vcc
	v_cmp_ngt_f32_e32 vcc, s4, v150
	s_nop 1
	v_cndmask_b32_e32 v172, v235, v165, vcc
	v_mul_f32_e32 v165, 0xbfb8aa3b, v152
	v_rndne_f32_e32 v168, v165
	v_sub_f32_e32 v169, v165, v168
	v_fma_f32 v165, v152, s22, -v165
	v_fmac_f32_e32 v165, 0xb2a5705f, v152
	v_add_f32_e32 v165, v169, v165
	v_exp_f32_e32 v165, v165
	v_cvt_i32_f32_e32 v168, v168
	v_cmp_nlt_f32_e32 vcc, s55, v152
	v_ldexp_f32 v165, v165, v168
	s_nop 0
	v_cndmask_b32_e32 v165, 0, v165, vcc
	v_cmp_ngt_f32_e32 vcc, s4, v152
	s_nop 1
	v_cndmask_b32_e32 v168, v235, v165, vcc
	v_mul_f32_e32 v165, 0xbfb8aa3b, v151
	v_rndne_f32_e32 v169, v165
	v_sub_f32_e32 v170, v165, v169
	v_fma_f32 v165, v151, s22, -v165
	v_fmac_f32_e32 v165, 0xb2a5705f, v151
	v_add_f32_e32 v165, v170, v165
	v_exp_f32_e32 v165, v165
	v_cvt_i32_f32_e32 v169, v169
	v_cmp_nlt_f32_e32 vcc, s55, v151
	v_ldexp_f32 v165, v165, v169
	s_nop 0
	v_cndmask_b32_e32 v165, 0, v165, vcc
	v_cmp_ngt_f32_e32 vcc, s4, v151
	s_nop 1
	v_cndmask_b32_e32 v173, v235, v165, vcc
	v_mul_f32_e32 v165, 0xbfb8aa3b, v153
	v_rndne_f32_e32 v169, v165
	v_sub_f32_e32 v170, v165, v169
	v_fma_f32 v165, v153, s22, -v165
	v_fmac_f32_e32 v165, 0xb2a5705f, v153
	v_add_f32_e32 v165, v170, v165
	v_exp_f32_e32 v165, v165
	v_cvt_i32_f32_e32 v169, v169
	v_cmp_nlt_f32_e32 vcc, s55, v153
	v_pk_add_f32 v[172:173], v[172:173], 1.0 op_sel_hi:[1,0]
	v_ldexp_f32 v165, v165, v169
; __device__ __forceinline__ void row_process(const RowArgs& R, int m, int lane, const RowRaw& q, const float (&gp)[2][8], const float (&gn)[2][8], const f32x4 bf, const LAS f32x4* afl) {
;     ...
;                 for (int c = 0; c < 8; ++c) v[j][c] += (1.0f / (1.0f + expf(-f[j][c]))) * (e[j][c] * r * gp[j][c]);
	v_cndmask_b32_e32 v165, 0, v165, vcc
	v_cmp_ngt_f32_e32 vcc, s4, v153
	s_nop 1
	v_cndmask_b32_e32 v169, v235, v165, vcc
	v_pk_add_f32 v[168:169], v[168:169], 1.0 op_sel_hi:[1,0]
	s_nop 0
	v_div_scale_f32 v165, s[14:15], v169, v169, 1.0
	v_rcp_f32_e32 v170, v165
	s_nop 0
	v_fma_f32 v171, -v165, v170, 1.0
	v_fmac_f32_e32 v170, v171, v170
	v_div_scale_f32 v171, vcc, 1.0, v169, 1.0
	v_mul_f32_e32 v174, v171, v170
	v_fma_f32 v175, -v165, v174, v171
	v_fmac_f32_e32 v174, v175, v170
	v_fma_f32 v165, -v165, v174, v171
	v_div_fmas_f32 v165, v165, v170, v174
	v_div_fixup_f32 v169, v165, v169, 1.0
	v_div_scale_f32 v165, s[14:15], v168, v168, 1.0
	v_rcp_f32_e32 v170, v165
	s_nop 0
	v_fma_f32 v171, -v165, v170, 1.0
	v_fmac_f32_e32 v170, v171, v170
	v_div_scale_f32 v171, vcc, 1.0, v168, 1.0
	v_mul_f32_e32 v174, v171, v170
	v_fma_f32 v175, -v165, v174, v171
	v_fmac_f32_e32 v174, v175, v170
	v_fma_f32 v165, -v165, v174, v171
	v_div_fmas_f32 v165, v165, v170, v174
	v_div_fixup_f32 v168, v165, v168, 1.0
	v_mul_f32_e32 v165, 0xbfb8aa3b, v163
	v_rndne_f32_e32 v170, v165
	v_sub_f32_e32 v171, v165, v170
	v_fma_f32 v165, v163, s22, -v165
	v_fmac_f32_e32 v165, 0xb2a5705f, v163
	v_add_f32_e32 v165, v171, v165
	v_exp_f32_e32 v165, v165
	v_cvt_i32_f32_e32 v170, v170
	v_cmp_nlt_f32_e32 vcc, s55, v163
	v_and_b32_e32 v175, 0xffff0000, v66
	v_ldexp_f32 v165, v165, v170
	v_cndmask_b32_e32 v165, 0, v165, vcc
	v_cmp_ngt_f32_e32 vcc, s4, v163
	s_nop 1
	v_cndmask_b32_e32 v171, v235, v165, vcc
	v_mul_f32_e32 v165, 0xbfb8aa3b, v156
	v_rndne_f32_e32 v170, v165
	v_sub_f32_e32 v174, v165, v170
	v_fma_f32 v165, v156, s22, -v165
	v_fmac_f32_e32 v165, 0xb2a5705f, v156
	v_add_f32_e32 v165, v174, v165
	v_exp_f32_e32 v165, v165
	v_cvt_i32_f32_e32 v170, v170
	v_cmp_nlt_f32_e32 vcc, s55, v156
	v_ldexp_f32 v165, v165, v170
	s_nop 0
	v_cndmask_b32_e32 v165, 0, v165, vcc
	v_cmp_ngt_f32_e32 vcc, s4, v156
	s_nop 1
	v_cndmask_b32_e32 v182, v235, v165, vcc
	v_mul_f32_e32 v165, 0xbfb8aa3b, v157
	v_rndne_f32_e32 v170, v165
	v_sub_f32_e32 v174, v165, v170
	v_fma_f32 v165, v157, s22, -v165
	v_fmac_f32_e32 v165, 0xb2a5705f, v157
	v_add_f32_e32 v165, v174, v165
	v_exp_f32_e32 v165, v165
	v_cvt_i32_f32_e32 v170, v170
	v_cmp_nlt_f32_e32 vcc, s55, v157
	v_ldexp_f32 v165, v165, v170
	s_nop 0
	v_cndmask_b32_e32 v165, 0, v165, vcc
	v_cmp_ngt_f32_e32 vcc, s4, v157
	s_nop 1
	v_cndmask_b32_e32 v183, v235, v165, vcc
	v_mul_f32_e32 v165, 0xbfb8aa3b, v158
	v_rndne_f32_e32 v170, v165
	v_sub_f32_e32 v174, v165, v170
	v_fma_f32 v165, v158, s22, -v165
	v_fmac_f32_e32 v165, 0xb2a5705f, v158
	v_add_f32_e32 v165, v174, v165
	v_exp_f32_e32 v165, v165
	v_cvt_i32_f32_e32 v170, v170
	v_cmp_nlt_f32_e32 vcc, s55, v158
	v_pk_add_f32 v[182:183], v[182:183], 1.0 op_sel_hi:[1,0]
	v_ldexp_f32 v165, v165, v170
	v_cndmask_b32_e32 v165, 0, v165, vcc
	v_cmp_ngt_f32_e32 vcc, s4, v158
	s_nop 1
	v_cndmask_b32_e32 v178, v235, v165, vcc
	v_mul_f32_e32 v165, 0xbfb8aa3b, v159
	v_rndne_f32_e32 v170, v165
	v_sub_f32_e32 v174, v165, v170
	v_fma_f32 v165, v159, s22, -v165
	v_fmac_f32_e32 v165, 0xb2a5705f, v159
	v_add_f32_e32 v165, v174, v165
	v_exp_f32_e32 v165, v165
	v_cvt_i32_f32_e32 v170, v170
	v_cmp_nlt_f32_e32 vcc, s55, v159
	v_ldexp_f32 v165, v165, v170
	s_nop 0
	v_cndmask_b32_e32 v165, 0, v165, vcc
	v_cmp_ngt_f32_e32 vcc, s4, v159
	s_nop 1
	v_cndmask_b32_e32 v179, v235, v165, vcc
	v_mul_f32_e32 v165, 0xbfb8aa3b, v160
	v_rndne_f32_e32 v170, v165
	v_sub_f32_e32 v174, v165, v170
	v_fma_f32 v165, v160, s22, -v165
	v_fmac_f32_e32 v165, 0xb2a5705f, v160
	v_add_f32_e32 v165, v174, v165
	v_exp_f32_e32 v165, v165
	v_cvt_i32_f32_e32 v170, v170
	v_cmp_nlt_f32_e32 vcc, s55, v160
	v_pk_add_f32 v[178:179], v[178:179], 1.0 op_sel_hi:[1,0]
	v_ldexp_f32 v165, v165, v170
	v_cndmask_b32_e32 v165, 0, v165, vcc
	v_cmp_ngt_f32_e32 vcc, s4, v160
	s_nop 1
	v_cndmask_b32_e32 v194, v235, v165, vcc
	v_mul_f32_e32 v165, 0xbfb8aa3b, v161
	v_rndne_f32_e32 v170, v165
	v_sub_f32_e32 v174, v165, v170
	v_fma_f32 v165, v161, s22, -v165
	v_fmac_f32_e32 v165, 0xb2a5705f, v161
	v_add_f32_e32 v165, v174, v165
	v_exp_f32_e32 v165, v165
	v_cvt_i32_f32_e32 v170, v170
	v_cmp_nlt_f32_e32 vcc, s55, v161
	v_lshlrev_b32_e32 v174, 16, v66
	v_pk_mul_f32 v[184:185], v[174:175], v[174:175]
	v_ldexp_f32 v165, v165, v170
	v_cndmask_b32_e32 v165, 0, v165, vcc
	v_cmp_ngt_f32_e32 vcc, s4, v161
	s_nop 1
	v_cndmask_b32_e32 v195, v235, v165, vcc
	v_div_scale_f32 v165, s[14:15], v179, v179, 1.0
	v_rcp_f32_e32 v170, v165
	s_nop 0
	v_fma_f32 v180, -v165, v170, 1.0
	v_fmac_f32_e32 v170, v180, v170
	v_div_scale_f32 v180, vcc, 1.0, v179, 1.0
	v_mul_f32_e32 v181, v180, v170
	v_fma_f32 v188, -v165, v181, v180
	v_fmac_f32_e32 v181, v188, v170
	v_fma_f32 v165, -v165, v181, v180
	v_div_fmas_f32 v165, v165, v170, v181
	v_div_fixup_f32 v179, v165, v179, 1.0
	v_div_scale_f32 v165, s[14:15], v178, v178, 1.0
	v_rcp_f32_e32 v170, v165
	s_nop 0
	v_fma_f32 v180, -v165, v170, 1.0
	v_fmac_f32_e32 v170, v180, v170
	v_div_scale_f32 v180, vcc, 1.0, v178, 1.0
	v_mul_f32_e32 v181, v180, v170
	v_fma_f32 v188, -v165, v181, v180
	v_fmac_f32_e32 v181, v188, v170
	v_fma_f32 v165, -v165, v181, v180
	v_div_fmas_f32 v165, v165, v170, v181
	v_div_fixup_f32 v178, v165, v178, 1.0
	v_div_scale_f32 v165, s[14:15], v183, v183, 1.0
	v_rcp_f32_e32 v170, v165
	v_lshlrev_b32_e32 v180, 16, v64
	v_and_b32_e32 v181, 0xffff0000, v64
	v_pk_mul_f32 v[192:193], v[180:181], v[180:181]
	v_fma_f32 v188, -v165, v170, 1.0
	v_fmac_f32_e32 v170, v188, v170
	v_div_scale_f32 v188, vcc, 1.0, v183, 1.0
	v_mul_f32_e32 v189, v188, v170
	v_fma_f32 v190, -v165, v189, v188
	v_fmac_f32_e32 v189, v190, v170
	v_fma_f32 v165, -v165, v189, v188
; #define UNPK_BF(dst, SRC_) do { const u32x4 t_ = (SRC_); dst[0] = bflo(t_.x); dst[1] = bfhi(t_.x); dst[2] = bflo(t_.y); dst[3] = bfhi(t_.y); dst[4] = bflo(t_.z); dst[5] = bfhi(t_.z); dst[6] = bflo(t_.w); dst[7] = bfhi(t_.w); } while (0)
; __device__ __forceinline__ void row_process(const RowArgs& R, int m, int lane, const RowRaw& q, const float (&gp)[2][8], const float (&gn)[2][8], const f32x4 bf, const LAS f32x4* afl) {
;     ...
;             for (int j = 0; j < 2; ++j) { UNPK_BF(e[j], q.e[j]);
; #pragma unroll
;                 for (int c = 0; c < 8; ++c) ss += e[j][c] * e[j][c]; }
;             const float r = 1.0f / sqrtf(wave_sum(ss) * (1.0f / DM) + EPS);
;     ...
;                 for (int c = 0; c < 8; ++c) v[j][c] += (1.0f / (1.0f + expf(-f[j][c]))) * (e[j][c] * r * gp[j][c]);
	v_div_fmas_f32 v165, v165, v170, v189
	v_div_fixup_f32 v183, v165, v183, 1.0
	v_div_scale_f32 v165, s[14:15], v182, v182, 1.0
	v_rcp_f32_e32 v170, v165
	s_nop 0
	v_fma_f32 v188, -v165, v170, 1.0
	v_fmac_f32_e32 v170, v188, v170
	v_div_scale_f32 v188, vcc, 1.0, v182, 1.0
	v_mul_f32_e32 v189, v188, v170
	v_fma_f32 v190, -v165, v189, v188
	v_fmac_f32_e32 v189, v190, v170
	v_fma_f32 v165, -v165, v189, v188
	v_div_fmas_f32 v165, v165, v170, v189
	v_div_fixup_f32 v182, v165, v182, 1.0
	v_div_scale_f32 v165, s[14:15], v173, v173, 1.0
	v_rcp_f32_e32 v170, v165
	v_and_b32_e32 v189, 0xffff0000, v62
	v_and_b32_e32 v188, 0xffff0000, v61
	v_pk_mul_f32 v[198:199], v[188:189], v[188:189]
	v_fma_f32 v190, -v165, v170, 1.0
	v_fmac_f32_e32 v170, v190, v170
	v_div_scale_f32 v190, vcc, 1.0, v173, 1.0
	v_mul_f32_e32 v191, v190, v170
	v_fma_f32 v197, -v165, v191, v190
	v_fmac_f32_e32 v191, v197, v170
	v_fma_f32 v165, -v165, v191, v190
	v_div_fmas_f32 v165, v165, v170, v191
	v_div_fixup_f32 v191, v165, v173, 1.0
	v_div_scale_f32 v165, s[14:15], v172, v172, 1.0
	v_rcp_f32_e32 v170, v165
	s_nop 0
	v_fma_f32 v173, -v165, v170, 1.0
	v_fmac_f32_e32 v170, v173, v170
	v_div_scale_f32 v173, vcc, 1.0, v172, 1.0
	v_mul_f32_e32 v190, v173, v170
	v_fma_f32 v197, -v165, v190, v173
	v_fmac_f32_e32 v190, v197, v170
	v_fma_f32 v165, -v165, v190, v173
	v_div_fmas_f32 v165, v165, v170, v190
	v_div_fixup_f32 v190, v165, v172, 1.0
	v_pk_add_f32 v[172:173], v[194:195], 1.0 op_sel_hi:[1,0]
	s_nop 0
	v_div_scale_f32 v165, s[14:15], v173, v173, 1.0
	v_rcp_f32_e32 v170, v165
	s_nop 0
	v_fma_f32 v194, -v165, v170, 1.0
	v_fmac_f32_e32 v170, v194, v170
	v_div_scale_f32 v194, vcc, 1.0, v173, 1.0
	v_mul_f32_e32 v195, v194, v170
	v_fma_f32 v197, -v165, v195, v194
	v_fmac_f32_e32 v195, v197, v170
	v_fma_f32 v165, -v165, v195, v194
	v_div_fmas_f32 v165, v165, v170, v195
	v_div_fixup_f32 v173, v165, v173, 1.0
	v_div_scale_f32 v165, s[14:15], v172, v172, 1.0
	v_rcp_f32_e32 v170, v165
	s_nop 0
	v_fma_f32 v194, -v165, v170, 1.0
	v_fmac_f32_e32 v170, v194, v170
	v_div_scale_f32 v194, vcc, 1.0, v172, 1.0
	v_mul_f32_e32 v195, v194, v170
	v_fma_f32 v197, -v165, v195, v194
	v_fmac_f32_e32 v195, v197, v170
	v_fma_f32 v165, -v165, v195, v194
	v_div_fmas_f32 v165, v165, v170, v195
	v_div_fixup_f32 v172, v165, v172, 1.0
	v_mul_f32_e32 v165, 0xbfb8aa3b, v162
	v_rndne_f32_e32 v170, v165
	v_sub_f32_e32 v194, v165, v170
	v_fma_f32 v165, v162, s22, -v165
	v_fmac_f32_e32 v165, 0xb2a5705f, v162
	v_add_f32_e32 v165, v194, v165
	v_exp_f32_e32 v165, v165
	v_cvt_i32_f32_e32 v170, v170
	v_cmp_nlt_f32_e32 vcc, s55, v162
	v_lshlrev_b32_e32 v194, 16, v67
	v_and_b32_e32 v195, 0xffff0000, v63
	v_ldexp_f32 v165, v165, v170
	v_cndmask_b32_e32 v165, 0, v165, vcc
	v_cmp_ngt_f32_e32 vcc, s4, v162
	s_nop 1
	v_cndmask_b32_e32 v170, v235, v165, vcc
	v_mov_b32_e32 v165, v194
	v_pk_mul_f32 v[200:201], v[164:165], v[164:165]
	v_fma_f32 v165, v143, v143, v208
	v_add_f32_e32 v165, v209, v165
	v_add_f32_e32 v165, v198, v165
	v_add_f32_e32 v165, v204, v165
	v_add_f32_e32 v165, v199, v165
	v_add_f32_e32 v165, v205, v165
	v_fmac_f32_e32 v165, v195, v195
	v_add_f32_e32 v165, v192, v165
	v_add_f32_e32 v165, v193, v165
	v_add_f32_e32 v165, v186, v165
	v_add_f32_e32 v165, v187, v165
	v_add_f32_e32 v165, v184, v165
	v_add_f32_e32 v165, v185, v165
	v_add_f32_e32 v165, v201, v165
	v_add_f32_e32 v165, v200, v165
	v_pk_add_f32 v[170:171], v[170:171], 1.0 op_sel_hi:[1,0]
	v_mov_b32_e32 v193, v164
	v_add_f32_dpp v165, v165, v165 quad_perm:[1,0,3,2] row_mask:0xf bank_mask:0xf bound_ctrl:1
	s_nop 1
	v_add_f32_dpp v165, v165, v165 quad_perm:[2,3,0,1] row_mask:0xf bank_mask:0xf bound_ctrl:1
	s_nop 1
	v_add_f32_dpp v165, v165, v165 row_half_mirror row_mask:0xf bank_mask:0xf bound_ctrl:1
	s_nop 1
	v_add_f32_dpp v165, v165, v165 row_mirror row_mask:0xf bank_mask:0xf bound_ctrl:1
	s_nop 0
	v_readlane_b32 s1, v165, 16
	v_readlane_b32 s3, v165, 48
	v_readlane_b32 s14, v165, 0
	v_readlane_b32 s15, v165, 32
	v_mov_b32_e32 v184, s1
	v_mov_b32_e32 v185, s3
	v_pk_add_f32 v[184:185], s[14:15], v[184:185]
	s_nop 0
	v_add_f32_e32 v165, v184, v185
	v_fmamk_f32 v165, v165, 0x3a800000, v229
	v_cmp_gt_f32_e32 vcc, s59, v165
	v_mul_f32_e32 v184, 0x4f800000, v165
	s_nop 0
	v_cndmask_b32_e32 v165, v165, v184, vcc
; __device__ __forceinline__ void row_process(const RowArgs& R, int m, int lane, const RowRaw& q, const float (&gp)[2][8], const float (&gn)[2][8], const f32x4 bf, const LAS f32x4* afl) {
;     ...
;             const float r = 1.0f / sqrtf(wave_sum(ss) * (1.0f / DM) + EPS);
; #pragma unroll
;             for (int j = 0; j < 2; ++j)
; #pragma unroll
;                 for (int c = 0; c < 8; ++c) v[j][c] += (1.0f / (1.0f + expf(-f[j][c]))) * (e[j][c] * r * gp[j][c]);
	v_sqrt_f32_e32 v184, v165
	s_nop 0
	v_add_u32_e32 v185, -1, v184
	v_fma_f32 v186, -v185, v184, v165
	v_cmp_ge_f32_e64 s[14:15], 0, v186
	v_add_u32_e32 v186, 1, v184
	s_nop 0
	v_cndmask_b32_e64 v185, v184, v185, s[14:15]
	v_fma_f32 v184, -v186, v184, v165
	v_cmp_lt_f32_e64 s[14:15], 0, v184
	s_nop 1
	v_cndmask_b32_e64 v184, v185, v186, s[14:15]
	v_mul_f32_e32 v185, 0x37800000, v184
	v_cndmask_b32_e32 v184, v184, v185, vcc
	v_cmp_class_f32_e32 vcc, v165, v230
	s_nop 1
	v_cndmask_b32_e32 v165, v184, v165, vcc
	v_div_scale_f32 v184, s[14:15], v165, v165, 1.0
	v_rcp_f32_e32 v185, v184
	s_nop 0
	v_fma_f32 v186, -v184, v185, 1.0
	v_fmac_f32_e32 v185, v186, v185
	v_div_scale_f32 v186, vcc, 1.0, v165, 1.0
	v_mul_f32_e32 v187, v186, v185
	v_fma_f32 v192, -v184, v187, v186
	v_fmac_f32_e32 v187, v192, v185
	v_fma_f32 v184, -v184, v187, v186
	v_div_fmas_f32 v184, v184, v185, v187
	v_div_fixup_f32 v187, v184, v165, 1.0
	v_div_scale_f32 v165, s[14:15], v155, v155, 1.0
	v_rcp_f32_e32 v184, v165
	v_mul_f32_e32 v143, v187, v143
	v_mov_b32_e32 v198, v187
	v_pk_mul_f32 v[176:177], v[198:199], v[176:177] op_sel_hi:[0,1]
	v_fma_f32 v185, -v165, v184, 1.0
	v_fmac_f32_e32 v184, v185, v184
	v_div_scale_f32 v185, vcc, 1.0, v155, 1.0
	v_mul_f32_e32 v186, v185, v184
	v_fma_f32 v192, -v165, v186, v185
	v_fmac_f32_e32 v186, v192, v184
	v_fma_f32 v165, -v165, v186, v185
	v_div_fmas_f32 v165, v165, v184, v186
	v_mul_f32_e32 v192, v196, v143
	v_div_scale_f32 v143, s[14:15], v171, v171, 1.0
	v_div_fixup_f32 v186, v165, v155, 1.0
	v_rcp_f32_e32 v155, v143
	v_pk_mul_f32 v[184:185], v[198:199], v[206:207] op_sel_hi:[0,1]
	v_pk_mul_f32 v[184:185], v[6:7], v[184:185]
	v_pk_mul_f32 v[176:177], v[22:23], v[176:177]
	v_pk_mul_f32 v[166:167], v[166:167], v[184:185]
	v_pk_mul_f32 v[184:185], v[198:199], v[188:189] op_sel_hi:[0,1]
	v_pk_mul_f32 v[188:189], v[198:199], v[202:203] op_sel_hi:[0,1]
	v_fma_f32 v165, -v143, v155, 1.0
	v_pk_mul_f32 v[188:189], v[12:13], v[188:189]
	v_fmac_f32_e32 v155, v165, v155
	v_div_scale_f32 v165, vcc, 1.0, v171, 1.0
	v_pk_mul_f32 v[168:169], v[168:169], v[188:189]
	v_mul_f32_e32 v188, v165, v155
	v_fma_f32 v189, -v143, v188, v165
	v_fmac_f32_e32 v188, v189, v155
	v_fma_f32 v143, -v143, v188, v165
	v_div_fmas_f32 v143, v143, v155, v188
	v_div_fixup_f32 v189, v143, v171, 1.0
	v_div_scale_f32 v143, s[14:15], v170, v170, 1.0
	v_rcp_f32_e32 v155, v143
	v_pk_mul_f32 v[176:177], v[178:179], v[176:177]
	v_pk_mul_f32 v[184:185], v[140:141], v[184:185]
	v_pk_mul_f32 v[174:175], v[198:199], v[174:175] op_sel_hi:[0,1]
	v_fma_f32 v165, -v143, v155, 1.0
	v_fmac_f32_e32 v155, v165, v155
	v_div_scale_f32 v165, vcc, 1.0, v170, 1.0
	v_mul_f32_e32 v171, v165, v155
	v_fma_f32 v188, -v143, v171, v165
	v_fmac_f32_e32 v171, v188, v155
	v_fma_f32 v143, -v143, v171, v165
	v_div_fmas_f32 v143, v143, v155, v171
	v_div_fixup_f32 v188, v143, v170, 1.0
	v_mul_f32_e32 v143, 0xbfb8aa3b, v154
	v_rndne_f32_e32 v155, v143
	v_sub_f32_e32 v165, v143, v155
	v_fma_f32 v143, v154, s22, -v143
	v_fmac_f32_e32 v143, 0xb2a5705f, v154
	v_add_f32_e32 v143, v165, v143
	v_exp_f32_e32 v143, v143
	v_cvt_i32_f32_e32 v155, v155
	v_cmp_nlt_f32_e32 vcc, s55, v154
	v_pk_mul_f32 v[170:171], v[198:199], v[194:195] op_sel_hi:[0,1]
	v_pk_mul_f32 v[184:185], v[190:191], v[184:185]
	v_ldexp_f32 v143, v143, v155
	v_cndmask_b32_e32 v143, 0, v143, vcc
	v_cmp_ngt_f32_e32 vcc, s4, v154
	v_pk_mul_f32 v[190:191], v[14:15], v[170:171]
	v_pk_mul_f32 v[170:171], v[198:199], v[180:181] op_sel_hi:[0,1]
	v_cndmask_b32_e32 v143, v235, v143, vcc
	v_add_f32_e32 v143, 1.0, v143
	v_div_scale_f32 v155, s[14:15], v143, v143, 1.0
	v_rcp_f32_e32 v165, v155
	v_pk_mul_f32 v[170:171], v[20:21], v[170:171]
	v_pk_mul_f32 v[174:175], v[28:29], v[174:175]
	v_pk_mul_f32 v[170:171], v[182:183], v[170:171]
	v_fma_f32 v178, -v155, v165, 1.0
	v_fmac_f32_e32 v165, v178, v165
	v_div_scale_f32 v178, vcc, 1.0, v143, 1.0
	v_mul_f32_e32 v179, v178, v165
	v_fma_f32 v180, -v155, v179, v178
	v_fmac_f32_e32 v179, v180, v165
	v_fma_f32 v155, -v155, v179, v178
	v_div_fmas_f32 v155, v155, v165, v179
	v_pk_mul_f32 v[174:175], v[172:173], v[174:175]
	v_pk_mul_f32 v[172:173], v[188:189], v[190:191]
	v_div_fixup_f32 v143, v155, v143, 1.0
	v_pk_mul_f32 v[164:165], v[186:187], v[192:193]
	s_cbranch_execnz .LBB0_265

; __device__ __forceinline__ void row_load(const RowArgs& R, int m, int lane, RowRaw& q) {
;     const size_t off = (size_t)m * DM + 8 * lane;
;     if (R.hin32) {
; #pragma unroll
;         for (int j = 0; j < 2; ++j) { q.v32[j][0] = __builtin_nontemporal_load((const f32x4*)(R.hin32 + off + 512 * j)); q.v32[j][1] = __builtin_nontemporal_load((const f32x4*)(R.hin32 + off + 512 * j + 4)); }
;     } else {
; #pragma unroll
;         for (int j = 0; j < 2; ++j) q.v16[j] = __builtin_nontemporal_load((const u32x4*)(R.hin16 + off + 512 * j));
;     }
;     if (R.F) {
; #pragma unroll
;         for (int j = 0; j < 2; ++j) q.f[j] = __builtin_nontemporal_load((const u32x4*)(R.F + off + 512 * j));
;     }
;     if (R.F2) {
; #pragma unroll
;         for (int j = 0; j < 2; ++j) q.e[j] = __builtin_nontemporal_load((const u32x4*)(R.F2 + off + 512 * j));
;     }
;     if (R.p) q.p = __builtin_nontemporal_load((const f32x4*)(R.p + (size_t)m * PLE + 4 * lane));
.LBB0_278:
	v_mov_b64_e32 v[134:135], v[58:59]
	v_mov_b64_e32 v[138:139], v[54:55]
	v_mov_b64_e32 v[126:127], v[42:43]
	v_mov_b64_e32 v[130:131], v[38:39]
	v_mov_b64_e32 v[132:133], v[56:57]
	v_mov_b64_e32 v[136:137], v[52:53]
	v_mov_b64_e32 v[124:125], v[40:41]
	v_mov_b64_e32 v[128:129], v[36:37]
.LBB0_279:
	s_and_b64 vcc, exec, s[12:13]
	s_cbranch_vccnz .Lrp_skipF
	v_lshl_add_u64 v[36:37], v[148:149], 1, s[20:21]
	global_load_dwordx4 v[72:75], v[36:37], off nt
	global_load_dwordx4 v[76:79], v[36:37], off offset:1024 nt
.Lrp_skipF:
	s_andn2_b64 vcc, exec, s[36:37]
	s_cbranch_vccnz .LBB0_281
	v_lshl_add_u64 v[36:37], v[148:149], 1, s[96:97]
	global_load_dwordx4 v[60:63], v[36:37], off nt
	global_load_dwordx4 v[64:67], v[36:37], off offset:1024 nt
